# v9 + phase D select: boundary-candidate ranking with one 64-bit compare per pair and a prefetched key (verified against the original ranks in a side build)
# speedup vs baseline: 1.0273x; 1.0017x over previous
.LBB0_745:
	s_or_b64 exec, exec, s[26:27]
	s_waitcnt lgkmcnt(0)
	v_mov_b32_e32 v1, 0
	v_cmp_ne_u32_e64 s[26:27], 0, v17
	v_mov_b32_e32 v3, 0
	v_mov_b32_e32 v5, 0
	v_mov_b32_e32 v7, 0
	s_and_saveexec_b64 s[64:65], s[26:27]
	s_cbranch_execz .LBB0_755
	s_waitcnt lgkmcnt(0)
	v_readfirstlane_b32 s33, v17
	v_mov_b32_e32 v26, v9
	v_not_b32_e32 v18, v134
	v_mov_b32_e32 v19, v0
	v_not_b32_e32 v20, v140
	v_mov_b32_e32 v21, v2
	v_not_b32_e32 v22, v142
	v_mov_b32_e32 v23, v4
	v_not_b32_e32 v24, v144
	v_mov_b32_e32 v25, v6
	ds_read_b32 v30, v26
	s_mov_b32 s34, -1
.Lrk_loop:
	s_waitcnt lgkmcnt(0)
	v_readfirstlane_b32 s35, v30
	v_add_u32_e32 v26, 4, v26
	ds_read_b32 v30, v26
	s_nop 1
	v_cmp_lt_u64_e64 s[36:37], v[18:19], s[34:35]
	v_cmp_lt_u64_e64 s[38:39], v[20:21], s[34:35]
	v_cmp_lt_u64_e64 s[40:41], v[22:23], s[34:35]
	v_cmp_lt_u64_e64 s[26:27], v[24:25], s[34:35]
	v_addc_co_u32_e64 v7, s[36:37], 0, v7, s[36:37]
	v_addc_co_u32_e64 v5, s[38:39], 0, v5, s[38:39]
	v_addc_co_u32_e64 v3, s[40:41], 0, v3, s[40:41]
	v_addc_co_u32_e64 v1, s[26:27], 0, v1, s[26:27]
	s_add_i32 s34, s34, -1
	s_add_i32 s33, s33, -1
	s_cmp_lg_u32 s33, 0
	s_cbranch_scc1 .Lrk_loop
	s_waitcnt lgkmcnt(0)
